# v24 with the FFN-up late group delayed 3 sleep units (about half a tile) instead of 2
# speedup vs baseline: 1.0038x; 1.0030x over previous
; __global__ void __launch_bounds__(512, 2) fwd(Args args) {
;     ...
;     if (IN(7)) { pg8::Gemm g{Xb, Wt_up, M, FF, DM, DM}; pg8::StaticOrder S; S.init(M, FF, G, bx); pg8::EpiBf16<2> E{Ub, FF};
;         pg8::gemm_phase<pg8::EpiBf16<2>, pg8::StaticOrder, true, true>(lds, g, S, E); }
.LBB0_1009:
	s_cmp_lt_i32 s78, 8
	s_cselect_b64 s[0:1], -1, 0
	s_and_b64 s[0:1], s[0:1], s[4:5]
	s_andn2_b64 vcc, exec, s[0:1]
	s_cbranch_vccnz .LBB0_1026
	s_cmpk_lg_i32 s96, 0x100
	s_cbranch_scc1 .Lstg7_done
	s_cmpk_lt_i32 s74, 0x80
	s_cbranch_scc1 .Lstg7_done
	s_sleep 127
	s_sleep 40
	s_sleep 127
	s_sleep 40
	s_sleep 127
	s_sleep 40

; __global__ void __launch_bounds__(512, 2) fwd(Args args) {
;     ...
;     if (IN(14)) { pg8::Gemm g{Xb, Wt_up + (size_t)DM * FF, M, FF, DM, DM}; pg8::StaticOrder S; S.init(M, FF, G, bx); pg8::EpiBf16<2> E{Ub, FF};
;         pg8::gemm_phase<pg8::EpiBf16<2>, pg8::StaticOrder, true, true>(lds, g, S, E); }
.LBB0_1614:
	s_cmp_lt_i32 s78, 15
	s_cselect_b64 s[0:1], -1, 0
	s_and_b64 s[0:1], s[0:1], s[4:5]
	s_andn2_b64 vcc, exec, s[0:1]
	s_cbranch_vccnz .LBB0_1631
	s_cmpk_lg_i32 s96, 0x100
	s_cbranch_scc1 .Lstg14_done
	s_cmpk_lt_i32 s74, 0x80
	s_cbranch_scc1 .Lstg14_done
	s_sleep 127
	s_sleep 40
	s_sleep 127
	s_sleep 40
	s_sleep 127
	s_sleep 40
